# grid syncs 2-10: cg barrier replaced by sharded 2-level counter barrier (per-blockIdx%8 arrival counters + release flags in wt_in0 zero padding rows)
# speedup vs baseline: 1.0623x; 1.0623x over previous
.LBB0_152:
.LBB0_153:
	v_and_b32_e32 v1, 0x3fffffff, v0
	v_cmp_eq_u32_e32 vcc, 0, v1
	s_waitcnt vmcnt(0)
	s_barrier
	s_and_saveexec_b64 s[4:5], vcc
	s_cbranch_execz .LBB0_163
	buffer_wbl2 sc1
	s_waitcnt vmcnt(0)
	s_load_dwordx2 s[6:7], s[0:1], 0xc8
	s_load_dword s3, s[0:1], 0x1b8
	s_and_b32 s8, s2, 7
	v_mov_b32_e32 v2, 1
	s_waitcnt lgkmcnt(0)
	s_add_u32 s6, s6, 0x2a4000
	s_addc_u32 s7, s7, 0
	s_sub_u32 s10, s3, s8
	s_add_u32 s10, s10, 7
	s_lshr_b32 s10, s10, 3
	s_mul_i32 s10, s10, 1
	s_min_u32 s3, s3, 8
	s_mul_i32 s3, s3, 1
	s_lshl_b32 s8, s8, 10
	v_mov_b32_e32 v1, s8
	global_atomic_add v3, v1, v2, s[6:7] sc0
	s_waitcnt vmcnt(0)
	v_readfirstlane_b32 s9, v3
	s_nop 3
	s_add_u32 s9, s9, 1
	s_cmp_lg_u32 s9, s10
	s_cbranch_scc1 .Lfs_wait_2
	v_mov_b32_e32 v1, 0x4000
	global_atomic_add v3, v1, v2, s[6:7] sc0
	s_waitcnt vmcnt(0)
	v_readfirstlane_b32 s9, v3
	s_nop 3
	s_add_u32 s9, s9, 1
	v_mov_b32_e32 v1, 0x5000
	s_cmp_lg_u32 s9, s3
	s_cbranch_scc1 .Lfs_topspin_2
	global_atomic_add v1, v2, s[6:7]
	s_branch .Lfs_grel_2
.Lfs_topspin_2:
	s_sleep 1
	global_load_dword v3, v1, s[6:7] sc1
	s_waitcnt vmcnt(0)
	v_readfirstlane_b32 s9, v3
	s_nop 3
	s_cmp_lt_u32 s9, 1
	s_cbranch_scc1 .Lfs_topspin_2
.Lfs_grel_2:
	s_add_u32 s11, s8, 0x8000
	v_mov_b32_e32 v1, s11
	global_atomic_add v1, v2, s[6:7]
	s_branch .Lfs_done_2
.Lfs_wait_2:
	s_add_u32 s11, s8, 0x8000
	v_mov_b32_e32 v1, s11

.Lfs_done_2:
	buffer_inv sc1
	s_waitcnt vmcnt(0)

.LBB0_285:
.LBB0_286:
	v_and_b32_e32 v1, 0x3fffffff, v0
	v_cmp_eq_u32_e32 vcc, 0, v1
	s_waitcnt vmcnt(0)
	s_barrier
	s_and_saveexec_b64 s[4:5], vcc
	s_cbranch_execz .LBB0_296
	buffer_wbl2 sc1
	s_waitcnt vmcnt(0)
	s_load_dwordx2 s[6:7], s[0:1], 0xc8
	s_load_dword s3, s[0:1], 0x1b8
	s_and_b32 s10, s2, 7
	v_mov_b32_e32 v2, 1
	s_waitcnt lgkmcnt(0)
	s_add_u32 s6, s6, 0x2a4000
	s_addc_u32 s7, s7, 0
	s_sub_u32 s12, s3, s10
	s_add_u32 s12, s12, 7
	s_lshr_b32 s12, s12, 3
	s_mul_i32 s12, s12, 2
	s_min_u32 s3, s3, 8
	s_mul_i32 s3, s3, 2
	s_lshl_b32 s10, s10, 10
	v_mov_b32_e32 v1, s10
	global_atomic_add v3, v1, v2, s[6:7] sc0
	s_waitcnt vmcnt(0)
	v_readfirstlane_b32 s11, v3
	s_nop 3
	s_add_u32 s11, s11, 1
	s_cmp_lg_u32 s11, s12
	s_cbranch_scc1 .Lfs_wait_3
	v_mov_b32_e32 v1, 0x4000
	global_atomic_add v3, v1, v2, s[6:7] sc0
	s_waitcnt vmcnt(0)
	v_readfirstlane_b32 s11, v3
	s_nop 3
	s_add_u32 s11, s11, 1
	v_mov_b32_e32 v1, 0x5000
	s_cmp_lg_u32 s11, s3
	s_cbranch_scc1 .Lfs_topspin_3
	global_atomic_add v1, v2, s[6:7]
	s_branch .Lfs_grel_3
.Lfs_topspin_3:
	s_sleep 1
	global_load_dword v3, v1, s[6:7] sc1
	s_waitcnt vmcnt(0)
	v_readfirstlane_b32 s11, v3
	s_nop 3
	s_cmp_lt_u32 s11, 2
	s_cbranch_scc1 .Lfs_topspin_3
.Lfs_grel_3:
	s_add_u32 s13, s10, 0x8000
	v_mov_b32_e32 v1, s13
	global_atomic_add v1, v2, s[6:7]
	s_branch .Lfs_done_3
.Lfs_wait_3:
	s_add_u32 s13, s10, 0x8000
	v_mov_b32_e32 v1, s13

.LBB0_324:
.LBB0_325:
	v_and_b32_e32 v1, 0x3fffffff, v0
	v_cmp_eq_u32_e32 vcc, 0, v1
	s_waitcnt vmcnt(0)
	s_barrier
	s_and_saveexec_b64 s[6:7], vcc
	s_cbranch_execz .LBB0_335
	buffer_wbl2 sc1
	s_waitcnt vmcnt(0)
	s_load_dwordx2 s[8:9], s[0:1], 0xc8
	s_load_dword s3, s[0:1], 0x1b8
	s_and_b32 s10, s2, 7
	v_mov_b32_e32 v2, 1
	s_waitcnt lgkmcnt(0)
	s_add_u32 s8, s8, 0x2a4000
	s_addc_u32 s9, s9, 0
	s_sub_u32 s12, s3, s10
	s_add_u32 s12, s12, 7
	s_lshr_b32 s12, s12, 3
	s_mul_i32 s12, s12, 3
	s_min_u32 s3, s3, 8
	s_mul_i32 s3, s3, 3
	s_lshl_b32 s10, s10, 10
	v_mov_b32_e32 v1, s10
	global_atomic_add v3, v1, v2, s[8:9] sc0
	s_waitcnt vmcnt(0)
	v_readfirstlane_b32 s11, v3
	s_nop 3
	s_add_u32 s11, s11, 1
	s_cmp_lg_u32 s11, s12
	s_cbranch_scc1 .Lfs_wait_4
	v_mov_b32_e32 v1, 0x4000
	global_atomic_add v3, v1, v2, s[8:9] sc0
	s_waitcnt vmcnt(0)
	v_readfirstlane_b32 s11, v3
	s_nop 3
	s_add_u32 s11, s11, 1
	v_mov_b32_e32 v1, 0x5000
	s_cmp_lg_u32 s11, s3
	s_cbranch_scc1 .Lfs_topspin_4
	global_atomic_add v1, v2, s[8:9]
	s_branch .Lfs_grel_4
.Lfs_topspin_4:
	s_sleep 1
	global_load_dword v3, v1, s[8:9] sc1
	s_waitcnt vmcnt(0)
	v_readfirstlane_b32 s11, v3
	s_nop 3
	s_cmp_lt_u32 s11, 3
	s_cbranch_scc1 .Lfs_topspin_4
.Lfs_grel_4:
	s_add_u32 s13, s10, 0x8000
	v_mov_b32_e32 v1, s13
	global_atomic_add v1, v2, s[8:9]
	s_branch .Lfs_done_4

.LBB0_342:
.LBB0_343:
	v_and_b32_e32 v1, 0x3fffffff, v0
	v_cmp_eq_u32_e32 vcc, 0, v1
	s_waitcnt lgkmcnt(0)
	s_waitcnt vmcnt(0)
	s_barrier
	s_and_saveexec_b64 s[4:5], vcc
	s_cbranch_execz .LBB0_353
	buffer_wbl2 sc1
	s_waitcnt vmcnt(0)
	s_load_dwordx2 s[8:9], s[0:1], 0xc8
	s_load_dword s3, s[0:1], 0x1b8
	s_and_b32 s10, s2, 7
	v_mov_b32_e32 v2, 1
	s_waitcnt lgkmcnt(0)
	s_add_u32 s8, s8, 0x2a4000
	s_addc_u32 s9, s9, 0
	s_sub_u32 s12, s3, s10
	s_add_u32 s12, s12, 7
	s_lshr_b32 s12, s12, 3
	s_mul_i32 s12, s12, 4
	s_min_u32 s3, s3, 8
	s_mul_i32 s3, s3, 4
	s_lshl_b32 s10, s10, 10
	v_mov_b32_e32 v1, s10
	global_atomic_add v3, v1, v2, s[8:9] sc0
	s_waitcnt vmcnt(0)
	v_readfirstlane_b32 s11, v3
	s_nop 3
	s_add_u32 s11, s11, 1
	s_cmp_lg_u32 s11, s12
	s_cbranch_scc1 .Lfs_wait_5
	v_mov_b32_e32 v1, 0x4000
	global_atomic_add v3, v1, v2, s[8:9] sc0
	s_waitcnt vmcnt(0)
	v_readfirstlane_b32 s11, v3
	s_nop 3
	s_add_u32 s11, s11, 1
	v_mov_b32_e32 v1, 0x5000
	s_cmp_lg_u32 s11, s3
	s_cbranch_scc1 .Lfs_topspin_5
	global_atomic_add v1, v2, s[8:9]
	s_branch .Lfs_grel_5
.Lfs_topspin_5:
	s_sleep 1
	global_load_dword v3, v1, s[8:9] sc1
	s_waitcnt vmcnt(0)
	v_readfirstlane_b32 s11, v3
	s_nop 3
	s_cmp_lt_u32 s11, 4
	s_cbranch_scc1 .Lfs_topspin_5

.LBB0_378:
.LBB0_379:
	v_and_b32_e32 v1, 0x3fffffff, v0
	v_cmp_eq_u32_e32 vcc, 0, v1
	s_waitcnt lgkmcnt(0)
	s_waitcnt vmcnt(0)
	s_barrier
	s_and_saveexec_b64 s[4:5], vcc
	s_cbranch_execz .LBB0_389
	buffer_wbl2 sc1
	s_waitcnt vmcnt(0)
	s_load_dwordx2 s[6:7], s[0:1], 0xc8
	s_load_dword s3, s[0:1], 0x1b8
	s_and_b32 s8, s2, 7
	v_mov_b32_e32 v2, 1
	s_waitcnt lgkmcnt(0)
	s_add_u32 s6, s6, 0x2a4000
	s_addc_u32 s7, s7, 0
	s_sub_u32 s12, s3, s8
	s_add_u32 s12, s12, 7
	s_lshr_b32 s12, s12, 3
	s_mul_i32 s12, s12, 5
	s_min_u32 s3, s3, 8
	s_mul_i32 s3, s3, 5
	s_lshl_b32 s8, s8, 10
	v_mov_b32_e32 v1, s8
	global_atomic_add v3, v1, v2, s[6:7] sc0
	s_waitcnt vmcnt(0)
	v_readfirstlane_b32 s9, v3
	s_nop 3
	s_add_u32 s9, s9, 1
	s_cmp_lg_u32 s9, s12
	s_cbranch_scc1 .Lfs_wait_6
	v_mov_b32_e32 v1, 0x4000
	global_atomic_add v3, v1, v2, s[6:7] sc0
	s_waitcnt vmcnt(0)
	v_readfirstlane_b32 s9, v3
	s_nop 3
	s_add_u32 s9, s9, 1
	v_mov_b32_e32 v1, 0x5000
	s_cmp_lg_u32 s9, s3
	s_cbranch_scc1 .Lfs_topspin_6
	global_atomic_add v1, v2, s[6:7]
	s_branch .Lfs_grel_6
.Lfs_topspin_6:
	s_sleep 1
	global_load_dword v3, v1, s[6:7] sc1
	s_waitcnt vmcnt(0)
	v_readfirstlane_b32 s9, v3
	s_nop 3
	s_cmp_lt_u32 s9, 5
	s_cbranch_scc1 .Lfs_topspin_6
.Lfs_grel_6:
	s_add_u32 s13, s8, 0x8000
	v_mov_b32_e32 v1, s13
	global_atomic_add v1, v2, s[6:7]
	s_branch .Lfs_done_6
.Lfs_wait_6:
	s_add_u32 s13, s8, 0x8000
	v_mov_b32_e32 v1, s13

.LBB0_457:
	v_and_b32_e32 v1, 0x3fffffff, v0
	v_cmp_eq_u32_e32 vcc, 0, v1
	s_waitcnt vmcnt(0)
	s_barrier
	s_and_saveexec_b64 s[4:5], vcc
	s_cbranch_execz .LBB0_467
	buffer_wbl2 sc1
	s_waitcnt vmcnt(0)
	s_load_dwordx2 s[6:7], s[0:1], 0xc8
	s_load_dword s3, s[0:1], 0x1b8
	s_and_b32 s8, s2, 7
	v_mov_b32_e32 v2, 1
	s_waitcnt lgkmcnt(0)
	s_add_u32 s6, s6, 0x2a4000
	s_addc_u32 s7, s7, 0
	s_sub_u32 s10, s3, s8
	s_add_u32 s10, s10, 7
	s_lshr_b32 s10, s10, 3
	s_mul_i32 s10, s10, 6
	s_min_u32 s3, s3, 8
	s_mul_i32 s3, s3, 6
	s_lshl_b32 s8, s8, 10
	v_mov_b32_e32 v1, s8
	global_atomic_add v3, v1, v2, s[6:7] sc0
	s_waitcnt vmcnt(0)
	v_readfirstlane_b32 s9, v3
	s_nop 3
	s_add_u32 s9, s9, 1
	s_cmp_lg_u32 s9, s10
	s_cbranch_scc1 .Lfs_wait_7
	v_mov_b32_e32 v1, 0x4000
	global_atomic_add v3, v1, v2, s[6:7] sc0
	s_waitcnt vmcnt(0)
	v_readfirstlane_b32 s9, v3
	s_nop 3
	s_add_u32 s9, s9, 1
	v_mov_b32_e32 v1, 0x5000
	s_cmp_lg_u32 s9, s3
	s_cbranch_scc1 .Lfs_topspin_7
	global_atomic_add v1, v2, s[6:7]
	s_branch .Lfs_grel_7
.Lfs_topspin_7:
	s_sleep 1
	global_load_dword v3, v1, s[6:7] sc1
	s_waitcnt vmcnt(0)
	v_readfirstlane_b32 s9, v3
	s_nop 3
	s_cmp_lt_u32 s9, 6
	s_cbranch_scc1 .Lfs_topspin_7

.LBB0_548:
.LBB0_549:
	v_and_b32_e32 v1, 0x3fffffff, v0
	v_cmp_eq_u32_e32 vcc, 0, v1
	s_waitcnt vmcnt(0)
	s_barrier
	s_and_saveexec_b64 s[4:5], vcc
	s_cbranch_execz .LBB0_559
	buffer_wbl2 sc1
	s_waitcnt vmcnt(0)
	s_load_dwordx2 s[8:9], s[0:1], 0xc8
	s_load_dword s3, s[0:1], 0x1b8
	s_and_b32 s10, s2, 7
	v_mov_b32_e32 v2, 1
	s_waitcnt lgkmcnt(0)
	s_add_u32 s8, s8, 0x2a4000
	s_addc_u32 s9, s9, 0
	s_sub_u32 s12, s3, s10
	s_add_u32 s12, s12, 7
	s_lshr_b32 s12, s12, 3
	s_mul_i32 s12, s12, 7
	s_min_u32 s3, s3, 8
	s_mul_i32 s3, s3, 7
	s_lshl_b32 s10, s10, 10
	v_mov_b32_e32 v1, s10
	global_atomic_add v3, v1, v2, s[8:9] sc0
	s_waitcnt vmcnt(0)
	v_readfirstlane_b32 s11, v3
	s_nop 3
	s_add_u32 s11, s11, 1
	s_cmp_lg_u32 s11, s12
	s_cbranch_scc1 .Lfs_wait_8
	v_mov_b32_e32 v1, 0x4000
	global_atomic_add v3, v1, v2, s[8:9] sc0
	s_waitcnt vmcnt(0)
	v_readfirstlane_b32 s11, v3
	s_nop 3
	s_add_u32 s11, s11, 1
	v_mov_b32_e32 v1, 0x5000
	s_cmp_lg_u32 s11, s3
	s_cbranch_scc1 .Lfs_topspin_8
	global_atomic_add v1, v2, s[8:9]
	s_branch .Lfs_grel_8
.Lfs_topspin_8:
	s_sleep 1
	global_load_dword v3, v1, s[8:9] sc1
	s_waitcnt vmcnt(0)
	v_readfirstlane_b32 s11, v3
	s_nop 3
	s_cmp_lt_u32 s11, 7
	s_cbranch_scc1 .Lfs_topspin_8

.LBB0_576:
.LBB0_577:
	v_and_b32_e32 v1, 0x3fffffff, v0
	v_cmp_eq_u32_e32 vcc, 0, v1
	s_waitcnt vmcnt(0)
	s_barrier
	s_and_saveexec_b64 s[6:7], vcc
	s_cbranch_execz .LBB0_587
	buffer_wbl2 sc1
	s_waitcnt vmcnt(0)
	s_load_dwordx2 s[8:9], s[0:1], 0xc8
	s_load_dword s3, s[0:1], 0x1b8
	s_and_b32 s10, s2, 7
	v_mov_b32_e32 v2, 1
	s_waitcnt lgkmcnt(0)
	s_add_u32 s8, s8, 0x2a4000
	s_addc_u32 s9, s9, 0
	s_sub_u32 s12, s3, s10
	s_add_u32 s12, s12, 7
	s_lshr_b32 s12, s12, 3
	s_mul_i32 s12, s12, 8
	s_min_u32 s3, s3, 8
	s_mul_i32 s3, s3, 8
	s_lshl_b32 s10, s10, 10
	v_mov_b32_e32 v1, s10
	global_atomic_add v3, v1, v2, s[8:9] sc0
	s_waitcnt vmcnt(0)
	v_readfirstlane_b32 s11, v3
	s_nop 3
	s_add_u32 s11, s11, 1
	s_cmp_lg_u32 s11, s12
	s_cbranch_scc1 .Lfs_wait_9
	v_mov_b32_e32 v1, 0x4000
	global_atomic_add v3, v1, v2, s[8:9] sc0
	s_waitcnt vmcnt(0)
	v_readfirstlane_b32 s11, v3
	s_nop 3
	s_add_u32 s11, s11, 1
	v_mov_b32_e32 v1, 0x5000
	s_cmp_lg_u32 s11, s3
	s_cbranch_scc1 .Lfs_topspin_9
	global_atomic_add v1, v2, s[8:9]
	s_branch .Lfs_grel_9
.Lfs_topspin_9:
	s_sleep 1
	global_load_dword v3, v1, s[8:9] sc1
	s_waitcnt vmcnt(0)
	v_readfirstlane_b32 s11, v3
	s_nop 3
	s_cmp_lt_u32 s11, 8
	s_cbranch_scc1 .Lfs_topspin_9

.LBB0_594:
.LBB0_595:
	v_and_b32_e32 v1, 0x3fffffff, v0
	v_cmp_eq_u32_e32 vcc, 0, v1
	s_waitcnt vmcnt(0)
	s_barrier
	s_and_saveexec_b64 s[4:5], vcc
	s_cbranch_execz .LBB0_605
	buffer_wbl2 sc1
	s_waitcnt vmcnt(0)
	s_load_dwordx2 s[6:7], s[0:1], 0xc8
	s_load_dword s3, s[0:1], 0x1b8
	s_and_b32 s8, s2, 7
	v_mov_b32_e32 v2, 1
	s_waitcnt lgkmcnt(0)
	s_add_u32 s6, s6, 0x2a4000
	s_addc_u32 s7, s7, 0
	s_sub_u32 s10, s3, s8
	s_add_u32 s10, s10, 7
	s_lshr_b32 s10, s10, 3
	s_mul_i32 s10, s10, 9
	s_min_u32 s3, s3, 8
	s_mul_i32 s3, s3, 9
	s_lshl_b32 s8, s8, 10
	v_mov_b32_e32 v1, s8
	global_atomic_add v3, v1, v2, s[6:7] sc0
	s_waitcnt vmcnt(0)
	v_readfirstlane_b32 s9, v3
	s_nop 3
	s_add_u32 s9, s9, 1
	s_cmp_lg_u32 s9, s10
	s_cbranch_scc1 .Lfs_wait_10
	v_mov_b32_e32 v1, 0x4000
	global_atomic_add v3, v1, v2, s[6:7] sc0
	s_waitcnt vmcnt(0)
	v_readfirstlane_b32 s9, v3
	s_nop 3
	s_add_u32 s9, s9, 1
	v_mov_b32_e32 v1, 0x5000
	s_cmp_lg_u32 s9, s3
	s_cbranch_scc1 .Lfs_topspin_10
	global_atomic_add v1, v2, s[6:7]
	s_branch .Lfs_grel_10
.Lfs_topspin_10:
	s_sleep 1
	global_load_dword v3, v1, s[6:7] sc1
	s_waitcnt vmcnt(0)
	v_readfirstlane_b32 s9, v3
	s_nop 3
	s_cmp_lt_u32 s9, 9
	s_cbranch_scc1 .Lfs_topspin_10
